# adds: first attention item of each workgroup is its own index (static), later items from the shared counter offset by 512: no queue contention at phase start and a fixed long+medium item pairing per C
# speedup vs baseline: 1.0183x; 1.0183x over previous
.LBB0_66:
	s_and_b64 vcc, exec, s[0:1]
	s_cbranch_vccz .LBB0_70
	s_cmp_gt_i32 s28, 0
	s_mov_b64 s[0:1], -1
	s_cbranch_scc0 .LBB0_569
	v_readlane_b32 s64, v251, 7
	s_cmp_gt_i32 s28, 1
	v_readlane_b32 s65, v251, 8
	v_readlane_b32 s66, v251, 9
	v_readlane_b32 s67, v251, 10
	s_cbranch_scc0 .LBB0_292
	s_lshl_b32 s0, s94, 6
	s_ashr_i32 s1, s0, 31
	s_lshl_b64 s[0:1], s[0:1], 2
	s_add_u32 s0, s64, s0
	s_addc_u32 s1, s65, s1
	s_add_u32 s0, s0, 0x3700
	s_addc_u32 s1, s1, 0
	v_writelane_b32 v254, s0, 35
	s_ashr_i32 s95, s94, 31
	v_readlane_b32 s4, v253, 58
	v_writelane_b32 v254, s1, 36
	s_lshl_b32 s0, s94, 2
	v_writelane_b32 v254, s0, 37
	s_lshl_b32 s0, s94, 1
	v_writelane_b32 v254, s0, 38
	s_lshl_b64 s[30:31], s[94:95], 2
	s_mul_i32 s1, s94, 0x1d10
	v_readlane_b32 s10, v254, 0
	s_mul_hi_i32 s0, s94, 0x1d10
	v_readlane_b32 s11, v254, 1
	s_add_u32 s1, s10, s1
	v_readlane_b32 s12, v254, 2
	v_readlane_b32 s13, v254, 3
	v_readlane_b32 s14, v254, 4
	v_readlane_b32 s15, v254, 5
	v_readlane_b32 s16, v254, 6
	v_readlane_b32 s17, v254, 7
	v_readlane_b32 s18, v254, 8
	v_readlane_b32 s19, v254, 9
	v_writelane_b32 v254, s1, 39
	s_addc_u32 s0, s11, s0
	v_writelane_b32 v254, s0, 40
	s_mov_b32 s0, s94
	v_writelane_b32 v254, s0, 41
	s_movk_i32 s26, 0xd0
	v_readlane_b32 s5, v253, 59
	v_writelane_b32 v254, s1, 42
	s_mov_b32 s0, s30
	v_writelane_b32 v254, s0, 43
	v_readlane_b32 s6, v253, 60
	v_readlane_b32 s7, v253, 61
	v_writelane_b32 v254, s1, 44
	v_readlane_b32 s8, v253, 62
	v_readlane_b32 s9, v253, 63
	s_mov_b32 s0, 1
	v_writelane_b32 v255, s0, 62
	s_branch .LBB0_75

.LBB0_75:
	v_mov_b32_e32 v2, v0
	s_barrier
	s_nop 0
	v_cmp_eq_u32_e32 vcc, 0, v2
	s_and_saveexec_b64 s[0:1], vcc
	s_cbranch_execz .LBB0_79
	s_mov_b64 s[4:5], exec
	v_mbcnt_lo_u32_b32 v2, s4, 0
	v_mbcnt_hi_u32_b32 v2, s5, v2
	v_cmp_eq_u32_e32 vcc, 0, v2
	s_and_saveexec_b64 s[2:3], vcc
	s_cbranch_execz .LBB0_78
	v_readlane_b32 vcc_lo, v255, 62
	s_nop 3
	s_cmp_eq_u32 vcc_lo, 0
	s_cbranch_scc1 .Ldq_shared
	v_readlane_b32 s4, v251, 0
	s_mov_b32 s5, 0
	v_writelane_b32 v255, s5, 62
	s_nop 3
	v_mov_b32_e32 v4, s4
	s_branch .LBB0_78
.Ldq_shared:
	s_bcnt1_i32_b64 s4, s[4:5]
	v_mov_b32_e32 v4, s4
	v_readlane_b32 s4, v254, 35
	v_readlane_b32 s5, v254, 36
	s_nop 4
	global_atomic_add v4, v3, v4, s[4:5] sc0
	s_waitcnt vmcnt(0)
	v_add_u32_e32 v4, 0x200, v4
